# P11 attention: partner-aware skew, wave w+4 starts QK s_sleep 8 later when its SIMD partner is active in the tile (v59 + attnskew2)
# baseline (speedup 1.0000x reference)
.LBB0_1340:
	v_cmp_eq_f32_e32 vcc, 0, v171
	s_nop 1
	s_cmp_eq_u64 vcc, exec
	s_cbranch_scc1 .LBB0_1346
	s_cmp_ge_i32 s12, s40
	s_cbranch_scc1 .LBB0_1346
	v_readfirstlane_b32 s98, v192
	s_cmpk_lt_u32 s98, 0x100
	s_cbranch_scc1 .Lattn_noskew
	s_sub_i32 s98, s40, 0x80
	s_cmp_ge_i32 s12, s98
	s_cbranch_scc1 .Lattn_noskew
	s_sleep 8
.Lattn_noskew:
	ds_read_b128 v[2:5], v204 offset:16384
	ds_read_b128 v[6:9], v204 offset:24576
	ds_read_b128 v[10:13], v205 offset:16384
	ds_read_b128 v[250:253], v205 offset:24576
	s_or_b32 s13, s12, 63
	s_mov_b64 s[10:11], -1
	s_cmp_lt_i32 s13, s39
	s_waitcnt lgkmcnt(3)
	v_mfma_f32_32x32x16_bf16 v[80:95], v[2:5], v[112:115], 0
	v_mbcnt_hi_u32_b32 v173, -1, v214
	ds_read_b128 v[2:5], v206 offset:16384
	s_waitcnt lgkmcnt(3)
	v_mfma_f32_32x32x16_bf16 v[96:111], v[6:9], v[112:115], 0
	ds_read_b128 v[6:9], v206 offset:24576
	s_waitcnt lgkmcnt(3)
	v_mfma_f32_32x32x16_bf16 v[80:95], v[10:13], v[116:119], v[80:95]
	ds_read_b128 v[10:13], v207 offset:16384
	s_waitcnt lgkmcnt(3)
	v_mfma_f32_32x32x16_bf16 v[96:111], v[250:253], v[116:119], v[96:111]
	ds_read_b128 v[250:253], v207 offset:24576
	s_waitcnt lgkmcnt(3)
	v_mfma_f32_32x32x16_bf16 v[80:95], v[2:5], v[120:123], v[80:95]
	ds_read_b128 v[2:5], v208 offset:16384
	s_waitcnt lgkmcnt(3)
	v_mfma_f32_32x32x16_bf16 v[96:111], v[6:9], v[120:123], v[96:111]
	ds_read_b128 v[6:9], v208 offset:24576
	s_waitcnt lgkmcnt(3)
	v_mfma_f32_32x32x16_bf16 v[80:95], v[10:13], v[124:127], v[80:95]
	ds_read_b128 v[10:13], v209 offset:24576
	s_waitcnt lgkmcnt(3)
	v_mfma_f32_32x32x16_bf16 v[96:111], v[250:253], v[124:127], v[96:111]
	ds_read_b128 v[250:253], v210 offset:24576
	s_waitcnt lgkmcnt(3)
	v_mfma_f32_32x32x16_bf16 v[80:95], v[2:5], v[128:131], v[80:95]
	ds_read_b128 v[2:5], v209 offset:16384
	s_waitcnt lgkmcnt(3)
	v_mfma_f32_32x32x16_bf16 v[96:111], v[6:9], v[128:131], v[96:111]
	ds_read_b128 v[6:9], v211 offset:24576
	s_waitcnt lgkmcnt(3)
	v_mfma_f32_32x32x16_bf16 v[96:111], v[10:13], v[132:135], v[96:111]
	ds_read_b128 v[10:13], v210 offset:16384
	s_waitcnt lgkmcnt(3)
	v_mfma_f32_32x32x16_bf16 v[96:111], v[250:253], v[136:139], v[96:111]
	ds_read_b128 v[250:253], v211 offset:16384
	s_waitcnt lgkmcnt(3)
	v_mfma_f32_32x32x16_bf16 v[80:95], v[2:5], v[132:135], v[80:95]
	s_waitcnt lgkmcnt(2)
	v_mfma_f32_32x32x16_bf16 v[96:111], v[6:9], v[140:143], v[96:111]
	s_waitcnt lgkmcnt(1)
	v_mfma_f32_32x32x16_bf16 v[80:95], v[10:13], v[136:139], v[80:95]
	s_nop 8
	v_max_f32_e32 v224, v96, v96
	v_max_f32_e32 v223, v97, v97
	v_max_f32_e32 v222, v98, v98
	v_max_f32_e32 v221, v99, v99
	v_max_f32_e32 v220, v100, v100
	v_max_f32_e32 v219, v101, v101
	v_max_f32_e32 v218, v102, v102
	s_waitcnt lgkmcnt(0)
	v_mfma_f32_32x32x16_bf16 v[80:95], v[250:253], v[140:143], v[80:95]
	v_max_f32_e32 v217, v103, v103
	v_max_f32_e32 v216, v104, v104
	v_max_f32_e32 v215, v105, v105
	v_max_f32_e32 v185, v106, v106
	v_max_f32_e32 v183, v107, v107
	v_max_f32_e32 v181, v108, v108
	v_max_f32_e32 v179, v109, v109
	v_max_f32_e32 v177, v110, v110
	v_max_f32_e32 v175, v111, v111
	s_nop 2
	v_max_f32_e32 v111, v80, v80
	v_max_f32_e32 v109, v81, v81
	v_max_f32_e32 v110, v82, v82
	v_max_f32_e32 v108, v83, v83
	v_max_f32_e32 v107, v84, v84
	v_max_f32_e32 v106, v85, v85
	v_max_f32_e32 v105, v86, v86
	v_max_f32_e32 v104, v87, v87
	v_max_f32_e32 v103, v88, v88
	v_max_f32_e32 v102, v89, v89
	v_max_f32_e32 v101, v90, v90
	v_max_f32_e32 v100, v91, v91
	v_max_f32_e32 v99, v92, v92
	v_max_f32_e32 v98, v93, v93
	v_max_f32_e32 v82, v94, v94
	v_max_f32_e32 v1, v95, v95
	s_cbranch_scc1 .LBB0_1343
	v_min_f32_e32 v2, 0x42c80000, v224
	v_exp_f32_e32 v2, v2
	v_min_f32_e32 v3, 0x42c80000, v223
	v_exp_f32_e32 v3, v3
	v_or_b32_e32 v90, s12, v196
	v_add_f32_e32 v4, 1.0, v2
	v_rcp_f32_e32 v4, v4
	v_or_b32_e32 v5, 32, v90
	v_cmp_lt_i32_e32 vcc, v5, v186
	v_min_f32_e32 v5, 0x42c80000, v222
	v_mul_f32_e32 v2, v2, v4
	v_cndmask_b32_e32 v83, 0, v2, vcc
	v_add_f32_e32 v2, 1.0, v3
	v_rcp_f32_e32 v2, v2
	v_exp_f32_e32 v5, v5
	v_cndmask_b32_e32 v11, 1.0, v4, vcc
	v_or_b32_e32 v4, 33, v90
	v_cmp_lt_i32_e32 vcc, v4, v186
	v_min_f32_e32 v4, 0x42c80000, v221
	v_exp_f32_e32 v4, v4
	v_cndmask_b32_e32 v15, 1.0, v2, vcc
	v_mul_f32_e32 v2, v3, v2
	v_cndmask_b32_e32 v88, 0, v2, vcc
	v_add_f32_e32 v2, 1.0, v5
	v_rcp_f32_e32 v2, v2
	v_or_b32_e32 v3, 34, v90
	v_cmp_lt_i32_e32 vcc, v3, v186
	v_or_b32_e32 v3, 35, v90
	v_min_f32_e32 v97, 0x42c80000, v175
	v_cndmask_b32_e32 v81, 1.0, v2, vcc
	v_mul_f32_e32 v2, v5, v2
	v_cndmask_b32_e32 v89, 0, v2, vcc
	v_add_f32_e32 v2, 1.0, v4
	v_rcp_f32_e32 v2, v2
	v_min_f32_e32 v5, 0x42c80000, v220
	v_exp_f32_e32 v5, v5
	v_cmp_lt_i32_e32 vcc, v3, v186
	v_or_b32_e32 v3, 40, v90
	v_exp_f32_e32 v97, v97
	v_cndmask_b32_e32 v85, 1.0, v2, vcc
	v_mul_f32_e32 v2, v4, v2
	v_cndmask_b32_e32 v91, 0, v2, vcc
	v_add_f32_e32 v2, 1.0, v5
	v_rcp_f32_e32 v2, v2
	v_min_f32_e32 v4, 0x42c80000, v219
	v_exp_f32_e32 v4, v4
	v_cmp_lt_i32_e32 vcc, v3, v186
	v_or_b32_e32 v3, 41, v90
	v_add_f32_e32 v227, 1.0, v97
	v_cndmask_b32_e32 v8, 1.0, v2, vcc
	v_mul_f32_e32 v2, v5, v2
	v_cndmask_b32_e32 v92, 0, v2, vcc
	v_add_f32_e32 v2, 1.0, v4
	v_rcp_f32_e32 v2, v2
	v_min_f32_e32 v5, 0x42c80000, v218
	v_exp_f32_e32 v5, v5
	v_cmp_lt_i32_e32 vcc, v3, v186
	v_or_b32_e32 v3, 42, v90
	v_rcp_f32_e32 v227, v227
	v_cndmask_b32_e32 v86, 1.0, v2, vcc
	v_mul_f32_e32 v2, v4, v2
	v_cndmask_b32_e32 v93, 0, v2, vcc
	v_add_f32_e32 v2, 1.0, v5
	v_rcp_f32_e32 v2, v2
	v_min_f32_e32 v4, 0x42c80000, v217
	v_exp_f32_e32 v4, v4
	v_cmp_lt_i32_e32 vcc, v3, v186
	v_or_b32_e32 v3, 43, v90
	v_and_b32_e32 v230, 64, v173
	v_cndmask_b32_e32 v87, 1.0, v2, vcc
	v_mul_f32_e32 v2, v5, v2
	v_cndmask_b32_e32 v94, 0, v2, vcc
	v_add_f32_e32 v2, 1.0, v4
	v_rcp_f32_e32 v2, v2
	v_min_f32_e32 v5, 0x42c80000, v216
	v_exp_f32_e32 v5, v5
	v_cmp_lt_i32_e32 vcc, v3, v186
	v_or_b32_e32 v3, 48, v90
	v_or_b32_e32 v226, 58, v90
	v_cndmask_b32_e32 v95, 1.0, v2, vcc
	v_mul_f32_e32 v2, v4, v2
	v_cndmask_b32_e32 v96, 0, v2, vcc
	v_add_f32_e32 v2, 1.0, v5
	v_rcp_f32_e32 v2, v2
	v_min_f32_e32 v4, 0x42c80000, v215
	v_exp_f32_e32 v4, v4
	v_cmp_lt_i32_e32 vcc, v3, v186
	v_or_b32_e32 v3, 49, v90
	v_or_b32_e32 v228, 59, v90
	v_cndmask_b32_e32 v6, 1.0, v2, vcc
	v_mul_f32_e32 v2, v5, v2
	v_cndmask_b32_e32 v12, 0, v2, vcc
	v_add_f32_e32 v2, 1.0, v4
	v_rcp_f32_e32 v2, v2
	v_min_f32_e32 v5, 0x42c80000, v185
	v_exp_f32_e32 v5, v5
	v_cmp_lt_i32_e32 vcc, v3, v186
	v_or_b32_e32 v3, 50, v90
	v_xor_b32_e32 v229, 32, v173
	v_cndmask_b32_e32 v7, 1.0, v2, vcc
	v_mul_f32_e32 v2, v4, v2
	v_cndmask_b32_e32 v9, 0, v2, vcc
	v_add_f32_e32 v2, 1.0, v5
	v_rcp_f32_e32 v2, v2
	v_min_f32_e32 v4, 0x42c80000, v183
	v_exp_f32_e32 v4, v4
	v_cmp_lt_i32_e32 vcc, v3, v186
	v_or_b32_e32 v3, 51, v90
	v_add_u32_e32 v230, 64, v230
	v_cndmask_b32_e32 v10, 1.0, v2, vcc
	v_mul_f32_e32 v2, v5, v2
	v_cndmask_b32_e32 v13, 0, v2, vcc
	v_add_f32_e32 v2, 1.0, v4
	v_rcp_f32_e32 v2, v2
	v_min_f32_e32 v5, 0x42c80000, v181
	v_exp_f32_e32 v5, v5
	v_cmp_lt_i32_e32 vcc, v3, v186
	v_or_b32_e32 v3, 56, v90
	v_cmp_lt_i32_e64 s[10:11], v228, v186
	v_cndmask_b32_e32 v14, 1.0, v2, vcc
	v_mul_f32_e32 v2, v4, v2
	v_cndmask_b32_e32 v84, 0, v2, vcc
	v_add_f32_e32 v2, 1.0, v5
	v_min_f32_e32 v4, 0x42c80000, v179
	v_rcp_f32_e32 v2, v2
	v_exp_f32_e32 v4, v4
	v_cmp_lt_i32_e32 vcc, v3, v186
	v_cmp_lt_i32_e64 s[12:13], v229, v230
	v_cndmask_b32_e64 v228, 1.0, v227, s[10:11]
	v_cndmask_b32_e32 v3, 1.0, v2, vcc
	v_mul_f32_e32 v2, v5, v2
	v_add_f32_e32 v5, 1.0, v4
	v_rcp_f32_e32 v5, v5
	v_cndmask_b32_e32 v80, 0, v2, vcc
	v_or_b32_e32 v2, 57, v90
	v_cmp_lt_i32_e32 vcc, v2, v186
	v_mul_f32_e32 v4, v4, v5
	v_cndmask_b32_e64 v229, v173, v229, s[12:13]
	v_cndmask_b32_e32 v2, 1.0, v5, vcc
	v_min_f32_e32 v5, 0x42c80000, v177
	v_exp_f32_e32 v5, v5
	v_cndmask_b32_e32 v4, 0, v4, vcc
	v_cmp_lt_i32_e32 vcc, v226, v186
	v_lshlrev_b32_e32 v231, 2, v229
	v_add_f32_e32 v225, 1.0, v5
	v_rcp_f32_e32 v225, v225
	v_mul_f32_e32 v3, v3, v2
	v_mul_f32_e32 v8, v8, v86
	v_cndmask_b32_e32 v226, 1.0, v225, vcc
	v_mul_f32_e32 v229, v226, v228
	v_mul_f32_e32 v229, v3, v229
	ds_bpermute_b32 v230, v231, v229
	v_mul_f32_e32 v3, v5, v225
	v_cndmask_b32_e32 v5, 0, v3, vcc
	v_mul_f32_e32 v3, v97, v227
	v_cndmask_b32_e64 v3, 0, v3, s[10:11]
	s_waitcnt lgkmcnt(0)
	v_mul_f32_e32 v97, v171, v230
	v_cndmask_b32_e64 v97, v171, v97, s[6:7]
	v_mul_f32_e32 v225, v228, v97
	v_mul_f32_e32 v226, v226, v225
	v_mul_f32_e32 v227, v2, v226
	v_mul_f32_e32 v2, v5, v225
	v_mul_f32_e32 v5, v6, v7
	v_mul_f32_e32 v6, v10, v14
	v_mul_f32_e32 v3, v3, v97
	v_mul_f32_e32 v97, v5, v6
	ds_bpermute_b32 v225, v231, v97
	v_mul_f32_e32 v6, v229, v230
	v_mul_f32_e32 v5, v4, v226
	v_mul_f32_e32 v4, v80, v227
	v_mul_f32_e32 v80, v171, v6
	s_waitcnt lgkmcnt(0)
	v_mul_f32_e32 v6, v80, v225
	v_cndmask_b32_e64 v6, v80, v6, s[6:7]
	v_mul_f32_e32 v14, v14, v6
	v_mul_f32_e32 v226, v10, v14
	v_mul_f32_e32 v10, v87, v95
	v_mul_f32_e32 v10, v8, v10
	v_mul_f32_e32 v227, v7, v226
	v_mul_f32_e32 v7, v84, v6
	v_mul_f32_e32 v6, v13, v14
	ds_bpermute_b32 v14, v231, v10
	v_mul_f32_e32 v84, v97, v225
	v_mul_f32_e32 v8, v12, v227
	v_pk_mul_f32 v[12:13], v[80:81], v[84:85]
	v_cmp_lt_i32_e32 vcc, v90, v186
	s_waitcnt lgkmcnt(0)
	v_mul_f32_e32 v80, v12, v14
	v_cndmask_b32_e64 v80, v12, v80, s[6:7]
	v_mul_f32_e32 v84, v95, v80
	v_mul_f32_e32 v95, v87, v84
	v_pk_mul_f32 v[10:11], v[10:11], v[14:15]
	v_mul_f32_e32 v97, v86, v95
	v_pk_mul_f32 v[86:87], v[10:11], v[12:13]
	ds_bpermute_b32 v225, v231, v87
	v_mul_f32_e32 v11, v96, v80
	v_mul_f32_e32 v10, v94, v84
	v_mul_f32_e32 v9, v9, v226
	v_mul_f32_e32 v12, v92, v97
	s_waitcnt lgkmcnt(0)
	v_mul_f32_e32 v14, v86, v225
	v_cndmask_b32_e64 v14, v86, v14, s[6:7]
	v_mul_f32_e32 v80, v85, v14
	v_mul_f32_e32 v81, v81, v80
	v_mul_f32_e32 v84, v15, v81
	v_mul_f32_e32 v15, v91, v14
	v_mul_f32_e32 v14, v89, v80
	v_min_f32_e32 v80, 0x42c80000, v111
	v_exp_f32_e32 v85, v80
	v_mul_f32_e32 v80, v83, v84
	v_min_f32_e32 v84, 0x42c80000, v109
	v_exp_f32_e32 v84, v84
	v_add_f32_e32 v83, 1.0, v85
	v_rcp_f32_e32 v83, v83
	v_mul_f32_e32 v81, v88, v81
	v_mul_f32_e32 v88, v87, v225
	v_min_f32_e32 v87, 0x42c80000, v110
	v_cndmask_b32_e32 v245, 1.0, v83, vcc
	v_mul_f32_e32 v83, v85, v83
	v_cndmask_b32_e32 v225, 0, v83, vcc
	v_add_f32_e32 v83, 1.0, v84
	v_rcp_f32_e32 v85, v83
	v_exp_f32_e32 v87, v87
	v_or_b32_e32 v83, 1, v90
	v_cmp_lt_i32_e32 vcc, v83, v186
	v_mul_f32_e32 v84, v84, v85
	v_min_f32_e32 v89, 0x42c80000, v108
	v_cndmask_b32_e32 v230, 0, v84, vcc
	v_add_f32_e32 v84, 1.0, v87
	v_rcp_f32_e32 v84, v84
	v_cndmask_b32_e32 v83, 1.0, v85, vcc
	v_or_b32_e32 v85, 2, v90
	v_exp_f32_e32 v89, v89
	v_cmp_lt_i32_e32 vcc, v85, v186
	v_or_b32_e32 v85, 3, v90
	v_mul_f32_e32 v13, v93, v95
	v_cndmask_b32_e32 v226, 1.0, v84, vcc
	v_mul_f32_e32 v84, v87, v84
	v_min_f32_e32 v87, 0x42c80000, v107
	v_exp_f32_e32 v87, v87
	v_cndmask_b32_e32 v227, 0, v84, vcc
	v_add_f32_e32 v84, 1.0, v89
	v_rcp_f32_e32 v84, v84
	v_cmp_lt_i32_e32 vcc, v85, v186
	v_add_f32_e32 v85, 1.0, v87
	v_rcp_f32_e32 v85, v85
	v_cndmask_b32_e32 v228, 1.0, v84, vcc
	v_mul_f32_e32 v84, v89, v84
	v_cndmask_b32_e32 v229, 0, v84, vcc
	v_or_b32_e32 v84, 8, v90
	v_cmp_lt_i32_e32 vcc, v84, v186
	v_mul_f32_e32 v84, v87, v85
	v_or_b32_e32 v89, 11, v90
	v_cndmask_b32_e32 v97, 1.0, v85, vcc
	v_min_f32_e32 v85, 0x42c80000, v106
	v_exp_f32_e32 v92, v85
	v_min_f32_e32 v85, 0x42c80000, v105
	v_cndmask_b32_e32 v96, 0, v84, vcc
	v_exp_f32_e32 v93, v85
	v_add_f32_e32 v84, 1.0, v92
	v_rcp_f32_e32 v94, v84
	v_min_f32_e32 v84, 0x42c80000, v104
	v_exp_f32_e32 v84, v84
	v_min_f32_e32 v85, 0x42c80000, v103
	v_exp_f32_e32 v85, v85
	v_add_f32_e32 v87, 1.0, v93
	v_rcp_f32_e32 v95, v87
	v_add_f32_e32 v87, 1.0, v84
	v_rcp_f32_e32 v232, v87
	v_add_f32_e32 v87, 1.0, v85
	v_rcp_f32_e32 v233, v87
	v_or_b32_e32 v87, 16, v90
	v_cmp_lt_i32_e64 s[10:11], v87, v169
	v_min_f32_e32 v87, 0x42c80000, v100
	v_exp_f32_e32 v238, v87
	v_min_f32_e32 v87, 0x42c80000, v99
	v_exp_f32_e32 v239, v87
	v_cmp_lt_i32_e32 vcc, v89, v186
	v_add_f32_e32 v87, 1.0, v238
	v_rcp_f32_e32 v240, v87
	v_add_f32_e32 v87, 1.0, v239
	v_rcp_f32_e32 v241, v87
	v_pk_mul_f32 v[84:85], v[84:85], v[232:233]
	v_or_b32_e32 v89, 19, v90
	v_cndmask_b32_e32 v247, 1.0, v232, vcc
	v_cndmask_b32_e32 v232, 0, v84, vcc
	v_or_b32_e32 v87, 24, v90
	v_cmp_lt_i32_e32 vcc, v89, v186
	v_min_f32_e32 v91, 0x42c80000, v98
	v_cndmask_b32_e64 v235, 1.0, v233, s[10:11]
	v_cndmask_b32_e64 v233, 0, v85, s[10:11]
	v_cndmask_b32_e32 v89, 1.0, v240, vcc
	v_cmp_lt_i32_e64 s[10:11], v87, v169
	v_pk_mul_f32 v[238:239], v[238:239], v[240:241]
	v_exp_f32_e32 v240, v91
	v_min_f32_e32 v91, 0x42c80000, v82
	v_cndmask_b32_e64 v87, 1.0, v241, s[10:11]
	v_exp_f32_e32 v241, v91
	v_min_f32_e32 v91, 0x42c80000, v1
	v_exp_f32_e32 v91, v91
	v_add_f32_e32 v234, 1.0, v240
	v_rcp_f32_e32 v242, v234
	v_add_f32_e32 v234, 1.0, v241
	v_add_f32_e32 v243, 1.0, v91
	v_rcp_f32_e32 v244, v243
	v_min_f32_e32 v85, 0x42c80000, v102
	v_rcp_f32_e32 v243, v234
	v_or_b32_e32 v234, 27, v90
	v_exp_f32_e32 v236, v85
	v_min_f32_e32 v85, 0x42c80000, v101
	v_cndmask_b32_e32 v238, 0, v238, vcc
	v_cmp_lt_i32_e32 vcc, v234, v186
	v_mul_f32_e32 v91, v91, v244
	v_exp_f32_e32 v237, v85
	v_cndmask_b32_e32 v248, 1.0, v244, vcc
	v_cndmask_b32_e32 v244, 0, v91, vcc
	v_or_b32_e32 v91, 26, v90
	v_or_b32_e32 v234, 25, v90
	v_cndmask_b32_e64 v239, 0, v239, s[10:11]
	v_cmp_lt_i32_e32 vcc, v234, v186
	v_cmp_lt_i32_e64 s[10:11], v91, v169
	v_add_f32_e32 v84, 1.0, v236
	v_cndmask_b32_e32 v249, 1.0, v242, vcc
	v_cndmask_b32_e64 v91, 1.0, v243, s[10:11]
	v_mul_f32_e32 v87, v87, v249
	v_mul_f32_e32 v234, v91, v248
	v_add_f32_e32 v85, 1.0, v237
	v_mul_f32_e32 v234, v87, v234
	v_rcp_f32_e32 v84, v84
	v_rcp_f32_e32 v85, v85
	v_pk_mul_f32 v[240:241], v[240:241], v[242:243]
	ds_bpermute_b32 v242, v231, v234
	v_or_b32_e32 v87, 18, v90
	v_or_b32_e32 v243, 17, v90
	v_cndmask_b32_e64 v241, 0, v241, s[10:11]
	v_cndmask_b32_e32 v240, 0, v240, vcc
	v_cmp_lt_i32_e32 vcc, v243, v186
	v_cmp_lt_i32_e64 s[10:11], v87, v169
	v_pk_mul_f32 v[92:93], v[92:93], v[94:95]
	v_cndmask_b32_e32 v243, 1.0, v84, vcc
	v_cndmask_b32_e64 v87, 1.0, v85, s[10:11]
	v_pk_mul_f32 v[84:85], v[236:237], v[84:85]
	s_waitcnt lgkmcnt(0)
	v_pk_mul_f32 v[234:235], v[234:235], v[242:243]
	v_cndmask_b32_e64 v237, 0, v85, s[10:11]
	v_cndmask_b32_e32 v236, 0, v84, vcc
	v_pk_mul_f32 v[84:85], v[86:87], v[88:89]
	v_mul_f32_e32 v245, v245, v83
	v_pk_mul_f32 v[234:235], v[234:235], v[84:85]
	v_mul_f32_e32 v86, v84, v242
	ds_bpermute_b32 v242, v231, v235
	v_cndmask_b32_e64 v246, v84, v86, s[6:7]
	v_mul_f32_e32 v85, v248, v246
	v_mul_f32_e32 v84, v91, v85
	v_mul_f32_e32 v249, v249, v84
	s_waitcnt lgkmcnt(0)
	v_mul_f32_e32 v86, v234, v242
	v_cndmask_b32_e64 v248, v234, v86, s[6:7]
	v_mul_f32_e32 v89, v89, v248
	v_mul_f32_e32 v88, v87, v89
	v_mul_f32_e32 v91, v243, v88
	v_pk_mul_f32 v[88:89], v[236:237], v[88:89]
	v_or_b32_e32 v237, 10, v90
	v_or_b32_e32 v90, 9, v90
	v_cmp_lt_i32_e32 vcc, v90, v186
	v_cmp_lt_i32_e64 s[10:11], v237, v169
	v_pk_mul_f32 v[86:87], v[238:239], v[248:249]
	v_cndmask_b32_e32 v236, 1.0, v94, vcc
	v_cndmask_b32_e64 v238, 1.0, v95, s[10:11]
	v_mul_f32_e32 v90, v97, v236
	v_mul_f32_e32 v97, v238, v247
	v_mul_f32_e32 v239, v90, v97
	ds_bpermute_b32 v237, v231, v239
	v_mul_f32_e32 v235, v235, v242
	v_mul_f32_e32 v97, v234, v235
	v_cndmask_b32_e64 v93, 0, v93, s[10:11]
	v_cndmask_b32_e32 v92, 0, v92, vcc
	s_waitcnt lgkmcnt(0)
	v_mul_f32_e32 v90, v97, v237
	v_cndmask_b32_e64 v90, v97, v90, s[6:7]
	v_mul_f32_e32 v235, v247, v90
	v_mul_f32_e32 v234, v238, v235
	v_mul_f32_e32 v247, v226, v228
	v_pk_mul_f32 v[94:95], v[92:93], v[234:235]
	v_pk_mul_f32 v[92:93], v[244:245], v[246:247]
	ds_bpermute_b32 v231, v231, v93
	v_mov_b32_e32 v235, v239
	v_pk_mul_f32 v[90:91], v[232:233], v[90:91]
	v_pk_mul_f32 v[232:233], v[234:235], v[236:237]
	v_pk_mul_f32 v[84:85], v[240:241], v[84:85]
	v_pk_mul_f32 v[96:97], v[96:97], v[232:233]
	s_mov_b64 s[10:11], 0
